# ssd_pass1: four per-token rs rows loaded together after the dt GEMV drains (one wait) instead of load+vmcnt(0) per masked block
# speedup vs baseline: 1.0074x; 1.0074x over previous
.LBB0_327:
	s_mov_b32 s70, 0xfffd0000
	s_mov_b32 s71, -1
	s_mov_b32 s72, 0xfffe0000
	s_mov_b32 s73, -1
	s_mov_b32 s74, 0xffff0000
	s_mov_b32 s75, -1
	v_lshl_add_u64 v[188:189], v[78:79], 0, s[70:71]
	v_lshl_add_u64 v[190:191], v[78:79], 0, s[72:73]
	v_lshl_add_u64 v[192:193], v[78:79], 0, s[74:75]
	v_mov_b64_e32 v[194:195], v[78:79]
	global_load_dwordx4 v[114:117], v[188:189], off offset:-768
	global_load_dwordx4 v[118:121], v[190:191], off offset:-768
	global_load_dwordx4 v[122:125], v[192:193], off offset:-768
	global_load_dwordx4 v[126:129], v[194:195], off offset:-768
	global_load_dwordx4 v[130:133], v[188:189], off offset:-512
	global_load_dwordx4 v[134:137], v[190:191], off offset:-512
	global_load_dwordx4 v[138:141], v[192:193], off offset:-512
	global_load_dwordx4 v[142:145], v[194:195], off offset:-512
	global_load_dwordx4 v[146:149], v[188:189], off offset:-256
	global_load_dwordx4 v[150:153], v[190:191], off offset:-256
	global_load_dwordx4 v[154:157], v[192:193], off offset:-256
	global_load_dwordx4 v[158:161], v[194:195], off offset:-256
	global_load_dwordx4 v[162:165], v[188:189], off
	global_load_dwordx4 v[176:179], v[190:191], off
	global_load_dwordx4 v[180:183], v[192:193], off
	global_load_dwordx4 v[184:187], v[194:195], off
	s_mov_b32 s5, 0xfffd0000
	v_add_co_u32_e32 v88, vcc, s5, v78
	v_add_u32_e32 v2, s4, v104
	s_nop 0
	v_addc_co_u32_e32 v89, vcc, -1, v79, vcc
	v_add_u32_e32 v60, 0x11000, v2
	ds_read_b128 v[72:75], v60
	v_add_u32_e32 v60, 0x11010, v2
	ds_read_b128 v[68:71], v60
	v_add_u32_e32 v60, 0x11020, v2
	ds_read_b128 v[64:67], v60
	v_add_u32_e32 v60, 0x11030, v2
	ds_read_b128 v[60:63], v60
	s_mov_b32 s5, 0xfffe0000
	s_addk_i32 s4, 0x1000
	s_mov_b64 s[6:7], 0x400
	s_cmpk_eq_i32 s4, 0x2000
	s_waitcnt vmcnt(15)
	v_mov_b64_e32 v[90:91], v[114:115]
	v_mov_b64_e32 v[92:93], v[116:117]
	global_load_dwordx4 v[114:117], v[188:189], off offset:256
	v_lshlrev_b32_e32 v94, 16, v90
	v_and_b32_e32 v90, 0xffff0000, v90
	v_lshlrev_b32_e32 v96, 16, v91
	v_and_b32_e32 v98, 0xffff0000, v91
	s_waitcnt lgkmcnt(3)
	v_pk_mul_f32 v[90:91], v[74:75], v[90:91] op_sel_hi:[1,0]
	v_lshlrev_b32_e32 v100, 16, v92
	v_pk_fma_f32 v[90:91], v[72:73], v[94:95], v[90:91] op_sel_hi:[1,0,1]
	v_and_b32_e32 v92, 0xffff0000, v92
	v_pk_add_f32 v[84:85], v[84:85], v[90:91]
	s_waitcnt lgkmcnt(2)
	v_pk_mul_f32 v[90:91], v[70:71], v[98:99] op_sel_hi:[1,0]
	v_and_b32_e32 v108, 0xffff0000, v93
	v_pk_fma_f32 v[90:91], v[68:69], v[96:97], v[90:91] op_sel_hi:[1,0,1]
	v_lshlrev_b32_e32 v106, 16, v93
	v_pk_add_f32 v[84:85], v[90:91], v[84:85]
	s_waitcnt lgkmcnt(1)
	v_pk_mul_f32 v[90:91], v[66:67], v[92:93] op_sel_hi:[1,0]
	s_nop 0
	v_pk_fma_f32 v[90:91], v[64:65], v[100:101], v[90:91] op_sel_hi:[1,0,1]
	s_nop 0
	v_pk_add_f32 v[84:85], v[90:91], v[84:85]
	s_waitcnt lgkmcnt(0)
	v_pk_mul_f32 v[90:91], v[62:63], v[108:109] op_sel_hi:[1,0]
	s_nop 0
	v_pk_fma_f32 v[90:91], v[60:61], v[106:107], v[90:91] op_sel_hi:[1,0,1]
	s_nop 0
	v_pk_add_f32 v[84:85], v[90:91], v[84:85]
	v_add_co_u32_e32 v90, vcc, s5, v78
	s_nop 1
	v_addc_co_u32_e32 v91, vcc, -1, v79, vcc
	s_waitcnt vmcnt(15)
	v_mov_b64_e32 v[92:93], v[118:119]
	v_mov_b64_e32 v[94:95], v[120:121]
	global_load_dwordx4 v[118:121], v[190:191], off offset:256
	v_lshlrev_b32_e32 v96, 16, v92
	v_and_b32_e32 v92, 0xffff0000, v92
	v_lshlrev_b32_e32 v98, 16, v93
	v_and_b32_e32 v100, 0xffff0000, v93
	v_pk_mul_f32 v[92:93], v[74:75], v[92:93] op_sel_hi:[1,0]
	v_lshlrev_b32_e32 v106, 16, v94
	v_pk_fma_f32 v[92:93], v[72:73], v[96:97], v[92:93] op_sel_hi:[1,0,1]
	v_and_b32_e32 v94, 0xffff0000, v94
	v_pk_add_f32 v[82:83], v[82:83], v[92:93]
	v_pk_mul_f32 v[92:93], v[70:71], v[100:101] op_sel_hi:[1,0]
	v_and_b32_e32 v110, 0xffff0000, v95
	v_pk_fma_f32 v[92:93], v[68:69], v[98:99], v[92:93] op_sel_hi:[1,0,1]
	v_lshlrev_b32_e32 v108, 16, v95
	v_pk_add_f32 v[82:83], v[92:93], v[82:83]
	v_pk_mul_f32 v[92:93], v[66:67], v[94:95] op_sel_hi:[1,0]
	s_nop 0
	v_pk_fma_f32 v[92:93], v[64:65], v[106:107], v[92:93] op_sel_hi:[1,0,1]
	s_nop 0
	v_pk_add_f32 v[82:83], v[92:93], v[82:83]
	v_pk_mul_f32 v[92:93], v[62:63], v[110:111] op_sel_hi:[1,0]
	s_nop 0
	v_pk_fma_f32 v[92:93], v[60:61], v[108:109], v[92:93] op_sel_hi:[1,0,1]
	s_nop 0
	v_pk_add_f32 v[94:95], v[92:93], v[82:83]
	v_add_co_u32_e32 v92, vcc, s33, v78
	s_nop 1
	v_addc_co_u32_e32 v93, vcc, -1, v79, vcc
	s_waitcnt vmcnt(15)
	v_mov_b64_e32 v[106:107], v[122:123]
	v_mov_b64_e32 v[108:109], v[124:125]
	global_load_dwordx4 v[122:125], v[192:193], off offset:256
	v_and_b32_e32 v96, 0xffff0000, v106
	v_lshlrev_b32_e32 v82, 16, v106
	v_pk_mul_f32 v[96:97], v[74:75], v[96:97] op_sel_hi:[1,0]
	v_and_b32_e32 v100, 0xffff0000, v107
	v_pk_fma_f32 v[82:83], v[72:73], v[82:83], v[96:97] op_sel_hi:[1,0,1]
	v_lshlrev_b32_e32 v98, 16, v107
	v_pk_add_f32 v[80:81], v[80:81], v[82:83]
	v_pk_mul_f32 v[82:83], v[70:71], v[100:101] op_sel_hi:[1,0]
	v_lshlrev_b32_e32 v106, 16, v108
	v_and_b32_e32 v108, 0xffff0000, v108
	v_pk_fma_f32 v[82:83], v[68:69], v[98:99], v[82:83] op_sel_hi:[1,0,1]
	v_and_b32_e32 v112, 0xffff0000, v109
	v_pk_add_f32 v[80:81], v[82:83], v[80:81]
	v_pk_mul_f32 v[82:83], v[66:67], v[108:109] op_sel_hi:[1,0]
	v_lshlrev_b32_e32 v110, 16, v109
	v_pk_fma_f32 v[82:83], v[64:65], v[106:107], v[82:83] op_sel_hi:[1,0,1]
	s_nop 0
	v_pk_add_f32 v[80:81], v[82:83], v[80:81]
	v_pk_mul_f32 v[82:83], v[62:63], v[112:113] op_sel_hi:[1,0]
	s_nop 0
	v_pk_fma_f32 v[82:83], v[60:61], v[110:111], v[82:83] op_sel_hi:[1,0,1]
	s_nop 0
	v_pk_add_f32 v[96:97], v[82:83], v[80:81]
	s_waitcnt vmcnt(15)
	v_mov_b64_e32 v[80:81], v[126:127]
	v_mov_b64_e32 v[82:83], v[128:129]
	global_load_dwordx4 v[126:129], v[194:195], off offset:256
	v_lshlrev_b32_e32 v108, 16, v82
	v_and_b32_e32 v82, 0xffff0000, v82
	v_and_b32_e32 v106, 0xffff0000, v81
	v_pk_mul_f32 v[66:67], v[66:67], v[82:83] op_sel_hi:[1,0]
	v_pk_mul_f32 v[70:71], v[70:71], v[106:107] op_sel_hi:[1,0]
	v_pk_fma_f32 v[64:65], v[64:65], v[108:109], v[66:67] op_sel_hi:[1,0,1]
	v_lshlrev_b32_e32 v98, 16, v80
	v_and_b32_e32 v80, 0xffff0000, v80
	v_pk_mul_f32 v[74:75], v[74:75], v[80:81] op_sel_hi:[1,0]
	v_lshlrev_b32_e32 v100, 16, v81
	v_pk_fma_f32 v[72:73], v[72:73], v[98:99], v[74:75] op_sel_hi:[1,0,1]
	v_and_b32_e32 v112, 0xffff0000, v83
	v_pk_add_f32 v[72:73], v[86:87], v[72:73]
	v_pk_fma_f32 v[68:69], v[68:69], v[100:101], v[70:71] op_sel_hi:[1,0,1]
	v_lshlrev_b32_e32 v110, 16, v83
	v_pk_add_f32 v[68:69], v[68:69], v[72:73]
	v_pk_mul_f32 v[62:63], v[62:63], v[112:113] op_sel_hi:[1,0]
	v_pk_add_f32 v[64:65], v[64:65], v[68:69]
	v_pk_fma_f32 v[60:61], v[60:61], v[110:111], v[62:63] op_sel_hi:[1,0,1]
	s_waitcnt vmcnt(15)
	v_mov_b64_e32 v[106:107], v[130:131]
	v_mov_b64_e32 v[108:109], v[132:133]
	global_load_dwordx4 v[130:133], v[188:189], off offset:512
	v_and_b32_e32 v86, 0xffff0000, v106
	v_pk_add_f32 v[80:81], v[60:61], v[64:65]
	v_add_u32_e32 v60, 0x11400, v2
	ds_read_b128 v[72:75], v60
	v_add_u32_e32 v60, 0x11410, v2
	ds_read_b128 v[68:71], v60
	v_add_u32_e32 v60, 0x11420, v2
	ds_read_b128 v[64:67], v60
	v_add_u32_e32 v60, 0x11430, v2
	v_lshlrev_b32_e32 v82, 16, v106
	s_waitcnt lgkmcnt(2)
	v_pk_mul_f32 v[86:87], v[74:75], v[86:87] op_sel_hi:[1,0]
	ds_read_b128 v[60:63], v60
	v_and_b32_e32 v100, 0xffff0000, v107
	v_pk_fma_f32 v[82:83], v[72:73], v[82:83], v[86:87] op_sel_hi:[1,0,1]
	v_lshlrev_b32_e32 v98, 16, v107
	v_pk_add_f32 v[82:83], v[84:85], v[82:83]
	s_waitcnt lgkmcnt(2)
	v_pk_mul_f32 v[84:85], v[70:71], v[100:101] op_sel_hi:[1,0]
	v_lshlrev_b32_e32 v106, 16, v108
	v_and_b32_e32 v108, 0xffff0000, v108
	v_pk_fma_f32 v[84:85], v[68:69], v[98:99], v[84:85] op_sel_hi:[1,0,1]
	v_and_b32_e32 v112, 0xffff0000, v109
	v_pk_add_f32 v[82:83], v[84:85], v[82:83]
	s_waitcnt lgkmcnt(1)
	v_pk_mul_f32 v[84:85], v[66:67], v[108:109] op_sel_hi:[1,0]
	v_lshlrev_b32_e32 v110, 16, v109
	v_pk_fma_f32 v[84:85], v[64:65], v[106:107], v[84:85] op_sel_hi:[1,0,1]
	s_nop 0
	v_pk_add_f32 v[82:83], v[84:85], v[82:83]
	s_waitcnt lgkmcnt(0)
	v_pk_mul_f32 v[84:85], v[62:63], v[112:113] op_sel_hi:[1,0]
	s_nop 0
	v_pk_fma_f32 v[84:85], v[60:61], v[110:111], v[84:85] op_sel_hi:[1,0,1]
	s_nop 0
	v_pk_add_f32 v[82:83], v[84:85], v[82:83]
	s_waitcnt vmcnt(15)
	v_mov_b64_e32 v[84:85], v[134:135]
	v_mov_b64_e32 v[86:87], v[136:137]
	global_load_dwordx4 v[134:137], v[190:191], off offset:512
	v_lshlrev_b32_e32 v98, 16, v84
	v_and_b32_e32 v84, 0xffff0000, v84
	v_lshlrev_b32_e32 v100, 16, v85
	v_and_b32_e32 v106, 0xffff0000, v85
	v_lshlrev_b32_e32 v108, 16, v86
	v_and_b32_e32 v86, 0xffff0000, v86
	v_pk_mul_f32 v[84:85], v[74:75], v[84:85] op_sel_hi:[1,0]
	v_lshlrev_b32_e32 v110, 16, v87
	v_and_b32_e32 v112, 0xffff0000, v87
	v_pk_fma_f32 v[84:85], v[72:73], v[98:99], v[84:85] op_sel_hi:[1,0,1]
	v_pk_mul_f32 v[86:87], v[66:67], v[86:87] op_sel_hi:[1,0]
	v_pk_add_f32 v[84:85], v[94:95], v[84:85]
	v_pk_mul_f32 v[94:95], v[70:71], v[106:107] op_sel_hi:[1,0]
	v_pk_fma_f32 v[86:87], v[64:65], v[108:109], v[86:87] op_sel_hi:[1,0,1]
	v_pk_fma_f32 v[94:95], v[68:69], v[100:101], v[94:95] op_sel_hi:[1,0,1]
	s_waitcnt vmcnt(15)
	v_mov_b64_e32 v[106:107], v[138:139]
	v_mov_b64_e32 v[108:109], v[140:141]
	global_load_dwordx4 v[138:141], v[192:193], off offset:512
	v_and_b32_e32 v100, 0xffff0000, v107
	v_pk_add_f32 v[84:85], v[94:95], v[84:85]
	v_and_b32_e32 v94, 0xffff0000, v106
	v_pk_add_f32 v[84:85], v[86:87], v[84:85]
	v_pk_mul_f32 v[86:87], v[62:63], v[112:113] op_sel_hi:[1,0]
	v_pk_mul_f32 v[94:95], v[74:75], v[94:95] op_sel_hi:[1,0]
	v_pk_fma_f32 v[86:87], v[60:61], v[110:111], v[86:87] op_sel_hi:[1,0,1]
	v_lshlrev_b32_e32 v98, 16, v107
	v_pk_add_f32 v[84:85], v[86:87], v[84:85]
	v_lshlrev_b32_e32 v86, 16, v106
	v_pk_fma_f32 v[86:87], v[72:73], v[86:87], v[94:95] op_sel_hi:[1,0,1]
	v_pk_mul_f32 v[94:95], v[70:71], v[100:101] op_sel_hi:[1,0]
	v_lshlrev_b32_e32 v106, 16, v108
	v_and_b32_e32 v108, 0xffff0000, v108
	v_pk_add_f32 v[86:87], v[96:97], v[86:87]
	v_pk_fma_f32 v[94:95], v[68:69], v[98:99], v[94:95] op_sel_hi:[1,0,1]
	v_and_b32_e32 v112, 0xffff0000, v109
	v_pk_add_f32 v[86:87], v[94:95], v[86:87]
	v_pk_mul_f32 v[94:95], v[66:67], v[108:109] op_sel_hi:[1,0]
	v_lshlrev_b32_e32 v110, 16, v109
	v_pk_fma_f32 v[94:95], v[64:65], v[106:107], v[94:95] op_sel_hi:[1,0,1]
	s_nop 0
	v_pk_add_f32 v[86:87], v[94:95], v[86:87]
	v_pk_mul_f32 v[94:95], v[62:63], v[112:113] op_sel_hi:[1,0]
	s_nop 0
	v_pk_fma_f32 v[94:95], v[60:61], v[110:111], v[94:95] op_sel_hi:[1,0,1]
	s_nop 0
	v_pk_add_f32 v[86:87], v[94:95], v[86:87]
	s_waitcnt vmcnt(15)
	v_mov_b64_e32 v[94:95], v[142:143]
	v_mov_b64_e32 v[96:97], v[144:145]
	global_load_dwordx4 v[142:145], v[194:195], off offset:512
	v_lshlrev_b32_e32 v98, 16, v94
	v_and_b32_e32 v94, 0xffff0000, v94
	v_lshlrev_b32_e32 v108, 16, v96
	v_and_b32_e32 v96, 0xffff0000, v96
	v_lshlrev_b32_e32 v100, 16, v95
	v_and_b32_e32 v106, 0xffff0000, v95
	v_lshlrev_b32_e32 v110, 16, v97
	v_and_b32_e32 v112, 0xffff0000, v97
	v_pk_mul_f32 v[74:75], v[74:75], v[94:95] op_sel_hi:[1,0]
	v_pk_mul_f32 v[66:67], v[66:67], v[96:97] op_sel_hi:[1,0]
	v_pk_fma_f32 v[72:73], v[72:73], v[98:99], v[74:75] op_sel_hi:[1,0,1]
	v_pk_mul_f32 v[70:71], v[70:71], v[106:107] op_sel_hi:[1,0]
	v_pk_add_f32 v[72:73], v[80:81], v[72:73]
	v_pk_fma_f32 v[68:69], v[68:69], v[100:101], v[70:71] op_sel_hi:[1,0,1]
	v_pk_fma_f32 v[64:65], v[64:65], v[108:109], v[66:67] op_sel_hi:[1,0,1]
	v_pk_add_f32 v[68:69], v[68:69], v[72:73]
	v_pk_mul_f32 v[62:63], v[62:63], v[112:113] op_sel_hi:[1,0]
	v_pk_add_f32 v[64:65], v[64:65], v[68:69]
	v_pk_fma_f32 v[60:61], v[60:61], v[110:111], v[62:63] op_sel_hi:[1,0,1]
	s_waitcnt vmcnt(15)
	v_mov_b64_e32 v[94:95], v[146:147]
	v_mov_b64_e32 v[96:97], v[148:149]
	global_load_dwordx4 v[146:149], v[188:189], off offset:768
	v_lshlrev_b32_e32 v98, 16, v94
	v_pk_add_f32 v[80:81], v[60:61], v[64:65]
	v_add_u32_e32 v60, 0x11800, v2
	ds_read_b128 v[72:75], v60
	v_add_u32_e32 v60, 0x11810, v2
	ds_read_b128 v[68:71], v60
	v_add_u32_e32 v60, 0x11820, v2
	ds_read_b128 v[64:67], v60
	v_and_b32_e32 v94, 0xffff0000, v94
	v_add_u32_e32 v60, 0x11830, v2
	v_lshlrev_b32_e32 v100, 16, v95
	v_and_b32_e32 v106, 0xffff0000, v95
	s_waitcnt lgkmcnt(2)
	v_pk_mul_f32 v[94:95], v[74:75], v[94:95] op_sel_hi:[1,0]
	ds_read_b128 v[60:63], v60
	v_pk_fma_f32 v[94:95], v[72:73], v[98:99], v[94:95] op_sel_hi:[1,0,1]
	v_lshlrev_b32_e32 v108, 16, v96
	v_pk_add_f32 v[82:83], v[82:83], v[94:95]
	s_waitcnt lgkmcnt(2)
	v_pk_mul_f32 v[94:95], v[70:71], v[106:107] op_sel_hi:[1,0]
	v_and_b32_e32 v96, 0xffff0000, v96
	v_pk_fma_f32 v[94:95], v[68:69], v[100:101], v[94:95] op_sel_hi:[1,0,1]
	v_and_b32_e32 v112, 0xffff0000, v97
	v_pk_add_f32 v[82:83], v[94:95], v[82:83]
	s_waitcnt lgkmcnt(1)
	v_pk_mul_f32 v[94:95], v[66:67], v[96:97] op_sel_hi:[1,0]
	v_lshlrev_b32_e32 v110, 16, v97
	v_pk_fma_f32 v[94:95], v[64:65], v[108:109], v[94:95] op_sel_hi:[1,0,1]
	s_nop 0
	v_pk_add_f32 v[82:83], v[94:95], v[82:83]
	s_waitcnt lgkmcnt(0)
	v_pk_mul_f32 v[94:95], v[62:63], v[112:113] op_sel_hi:[1,0]
	s_nop 0
	v_pk_fma_f32 v[94:95], v[60:61], v[110:111], v[94:95] op_sel_hi:[1,0,1]
	s_nop 0
	v_pk_add_f32 v[82:83], v[94:95], v[82:83]
	s_waitcnt vmcnt(15)
	v_mov_b64_e32 v[94:95], v[150:151]
	v_mov_b64_e32 v[96:97], v[152:153]
	global_load_dwordx4 v[150:153], v[190:191], off offset:768
	v_lshlrev_b32_e32 v98, 16, v94
	v_and_b32_e32 v94, 0xffff0000, v94
	v_lshlrev_b32_e32 v100, 16, v95
	v_and_b32_e32 v106, 0xffff0000, v95
	v_pk_mul_f32 v[94:95], v[74:75], v[94:95] op_sel_hi:[1,0]
	v_lshlrev_b32_e32 v108, 16, v96
	v_pk_fma_f32 v[94:95], v[72:73], v[98:99], v[94:95] op_sel_hi:[1,0,1]
	v_and_b32_e32 v96, 0xffff0000, v96
	v_pk_add_f32 v[84:85], v[84:85], v[94:95]
	v_pk_mul_f32 v[94:95], v[70:71], v[106:107] op_sel_hi:[1,0]
	v_and_b32_e32 v112, 0xffff0000, v97
	v_pk_fma_f32 v[94:95], v[68:69], v[100:101], v[94:95] op_sel_hi:[1,0,1]
	v_lshlrev_b32_e32 v110, 16, v97
	v_pk_add_f32 v[84:85], v[94:95], v[84:85]
	v_pk_mul_f32 v[94:95], v[66:67], v[96:97] op_sel_hi:[1,0]
	s_nop 0
	v_pk_fma_f32 v[94:95], v[64:65], v[108:109], v[94:95] op_sel_hi:[1,0,1]
	v_pk_add_f32 v[84:85], v[94:95], v[84:85]
	v_pk_mul_f32 v[94:95], v[62:63], v[112:113] op_sel_hi:[1,0]
	s_waitcnt vmcnt(15)
	v_mov_b64_e32 v[106:107], v[154:155]
	v_mov_b64_e32 v[108:109], v[156:157]
	global_load_dwordx4 v[154:157], v[192:193], off offset:768
	v_and_b32_e32 v96, 0xffff0000, v106
	v_pk_fma_f32 v[94:95], v[60:61], v[110:111], v[94:95] op_sel_hi:[1,0,1]
	v_pk_mul_f32 v[96:97], v[74:75], v[96:97] op_sel_hi:[1,0]
	v_pk_add_f32 v[94:95], v[94:95], v[84:85]
	v_lshlrev_b32_e32 v84, 16, v106
	v_and_b32_e32 v100, 0xffff0000, v107
	v_pk_fma_f32 v[84:85], v[72:73], v[84:85], v[96:97] op_sel_hi:[1,0,1]
	v_lshlrev_b32_e32 v98, 16, v107
	v_pk_add_f32 v[84:85], v[86:87], v[84:85]
	v_pk_mul_f32 v[86:87], v[70:71], v[100:101] op_sel_hi:[1,0]
	v_lshlrev_b32_e32 v106, 16, v108
	v_and_b32_e32 v108, 0xffff0000, v108
	v_pk_fma_f32 v[86:87], v[68:69], v[98:99], v[86:87] op_sel_hi:[1,0,1]
	v_and_b32_e32 v112, 0xffff0000, v109
	v_pk_add_f32 v[84:85], v[86:87], v[84:85]
	v_pk_mul_f32 v[86:87], v[66:67], v[108:109] op_sel_hi:[1,0]
	v_lshlrev_b32_e32 v110, 16, v109
	v_pk_fma_f32 v[86:87], v[64:65], v[106:107], v[86:87] op_sel_hi:[1,0,1]
	s_nop 0
	v_pk_add_f32 v[84:85], v[86:87], v[84:85]
	v_pk_mul_f32 v[86:87], v[62:63], v[112:113] op_sel_hi:[1,0]
	s_nop 0
	v_pk_fma_f32 v[86:87], v[60:61], v[110:111], v[86:87] op_sel_hi:[1,0,1]
	s_nop 0
	v_pk_add_f32 v[96:97], v[86:87], v[84:85]
	s_waitcnt vmcnt(15)
	v_mov_b64_e32 v[84:85], v[158:159]
	v_mov_b64_e32 v[86:87], v[160:161]
	global_load_dwordx4 v[158:161], v[194:195], off offset:768
	v_lshlrev_b32_e32 v108, 16, v86
	v_and_b32_e32 v86, 0xffff0000, v86
	v_and_b32_e32 v106, 0xffff0000, v85
	v_pk_mul_f32 v[66:67], v[66:67], v[86:87] op_sel_hi:[1,0]
	v_pk_mul_f32 v[70:71], v[70:71], v[106:107] op_sel_hi:[1,0]
	v_pk_fma_f32 v[64:65], v[64:65], v[108:109], v[66:67] op_sel_hi:[1,0,1]
	v_lshlrev_b32_e32 v98, 16, v84
	v_and_b32_e32 v84, 0xffff0000, v84
	v_pk_mul_f32 v[74:75], v[74:75], v[84:85] op_sel_hi:[1,0]
	v_lshlrev_b32_e32 v100, 16, v85
	v_pk_fma_f32 v[72:73], v[72:73], v[98:99], v[74:75] op_sel_hi:[1,0,1]
	v_and_b32_e32 v112, 0xffff0000, v87
	v_pk_add_f32 v[72:73], v[80:81], v[72:73]
	v_pk_fma_f32 v[68:69], v[68:69], v[100:101], v[70:71] op_sel_hi:[1,0,1]
	v_lshlrev_b32_e32 v110, 16, v87
	v_pk_add_f32 v[68:69], v[68:69], v[72:73]
	v_pk_mul_f32 v[62:63], v[62:63], v[112:113] op_sel_hi:[1,0]
	v_pk_add_f32 v[64:65], v[64:65], v[68:69]
	v_pk_fma_f32 v[60:61], v[60:61], v[110:111], v[62:63] op_sel_hi:[1,0,1]
	s_waitcnt vmcnt(15)
	v_mov_b64_e32 v[106:107], v[162:163]
	v_mov_b64_e32 v[108:109], v[164:165]
	global_load_dwordx4 v[162:165], v[188:189], off offset:1024
	v_and_b32_e32 v80, 0xffff0000, v106
	v_pk_add_f32 v[86:87], v[60:61], v[64:65]
	v_add_u32_e32 v60, 0x11c00, v2
	ds_read_b128 v[72:75], v60
	v_add_u32_e32 v60, 0x11c10, v2
	ds_read_b128 v[68:71], v60
	v_add_u32_e32 v60, 0x11c20, v2
	ds_read_b128 v[64:67], v60
	v_add_u32_e32 v2, 0x11c30, v2
	ds_read_b128 v[60:63], v2
	v_lshlrev_b32_e32 v2, 16, v106
	s_waitcnt lgkmcnt(3)
	v_pk_mul_f32 v[80:81], v[74:75], v[80:81] op_sel_hi:[1,0]
	v_and_b32_e32 v88, 0xffff0000, v107
	v_pk_fma_f32 v[80:81], v[72:73], v[2:3], v[80:81] op_sel_hi:[1,0,1]
	v_lshlrev_b32_e32 v84, 16, v107
	v_pk_add_f32 v[80:81], v[82:83], v[80:81]
	s_waitcnt lgkmcnt(2)
	v_pk_mul_f32 v[82:83], v[70:71], v[88:89] op_sel_hi:[1,0]
	v_and_b32_e32 v100, 0xffff0000, v108
	v_pk_fma_f32 v[82:83], v[68:69], v[84:85], v[82:83] op_sel_hi:[1,0,1]
	v_lshlrev_b32_e32 v98, 16, v108
	v_pk_add_f32 v[80:81], v[82:83], v[80:81]
	s_waitcnt lgkmcnt(1)
	v_pk_mul_f32 v[82:83], v[66:67], v[100:101] op_sel_hi:[1,0]
	v_and_b32_e32 v108, 0xffff0000, v109
	v_pk_fma_f32 v[82:83], v[64:65], v[98:99], v[82:83] op_sel_hi:[1,0,1]
	v_lshlrev_b32_e32 v106, 16, v109
	v_pk_add_f32 v[80:81], v[82:83], v[80:81]
	s_waitcnt lgkmcnt(0)
	v_pk_mul_f32 v[82:83], v[62:63], v[108:109] op_sel_hi:[1,0]
	s_nop 0
	v_pk_fma_f32 v[82:83], v[60:61], v[106:107], v[82:83] op_sel_hi:[1,0,1]
	s_nop 0
	v_pk_add_f32 v[84:85], v[82:83], v[80:81]
	s_waitcnt vmcnt(15)
	v_mov_b64_e32 v[80:81], v[176:177]
	v_mov_b64_e32 v[82:83], v[178:179]
	global_load_dwordx4 v[176:179], v[190:191], off offset:1024
	v_lshlrev_b32_e32 v2, 16, v80
	v_and_b32_e32 v80, 0xffff0000, v80
	v_lshlrev_b32_e32 v88, 16, v81
	v_and_b32_e32 v90, 0xffff0000, v81
	v_pk_mul_f32 v[80:81], v[74:75], v[80:81] op_sel_hi:[1,0]
	v_pk_mul_f32 v[90:91], v[70:71], v[90:91] op_sel_hi:[1,0]
	v_pk_fma_f32 v[80:81], v[72:73], v[2:3], v[80:81] op_sel_hi:[1,0,1]
	v_pk_fma_f32 v[88:89], v[68:69], v[88:89], v[90:91] op_sel_hi:[1,0,1]
	v_pk_add_f32 v[80:81], v[94:95], v[80:81]
	v_lshlrev_b32_e32 v98, 16, v82
	v_pk_add_f32 v[80:81], v[88:89], v[80:81]
	v_and_b32_e32 v82, 0xffff0000, v82
	v_lshlrev_b32_e32 v100, 16, v83
	v_and_b32_e32 v106, 0xffff0000, v83
	v_pk_mul_f32 v[82:83], v[66:67], v[82:83] op_sel_hi:[1,0]
	s_waitcnt vmcnt(15)
	v_mov_b64_e32 v[88:89], v[180:181]
	v_mov_b64_e32 v[90:91], v[182:183]
	global_load_dwordx4 v[180:183], v[192:193], off offset:1024
	v_lshlrev_b32_e32 v2, 16, v88
	v_pk_fma_f32 v[82:83], v[64:65], v[98:99], v[82:83] op_sel_hi:[1,0,1]
	v_and_b32_e32 v92, 0xffff0000, v89
	v_pk_add_f32 v[80:81], v[82:83], v[80:81]
	v_pk_mul_f32 v[82:83], v[62:63], v[106:107] op_sel_hi:[1,0]
	v_pk_mul_f32 v[92:93], v[70:71], v[92:93] op_sel_hi:[1,0]
	v_pk_fma_f32 v[82:83], v[60:61], v[100:101], v[82:83] op_sel_hi:[1,0,1]
	v_lshlrev_b32_e32 v94, 16, v90
	v_pk_add_f32 v[82:83], v[82:83], v[80:81]
	v_and_b32_e32 v80, 0xffff0000, v88
	v_pk_mul_f32 v[80:81], v[74:75], v[80:81] op_sel_hi:[1,0]
	v_lshlrev_b32_e32 v88, 16, v89
	v_pk_fma_f32 v[80:81], v[72:73], v[2:3], v[80:81] op_sel_hi:[1,0,1]
	v_and_b32_e32 v90, 0xffff0000, v90
	v_pk_add_f32 v[80:81], v[96:97], v[80:81]
	v_pk_fma_f32 v[88:89], v[68:69], v[88:89], v[92:93] op_sel_hi:[1,0,1]
	v_lshlrev_b32_e32 v98, 16, v91
	v_and_b32_e32 v100, 0xffff0000, v91
	v_pk_add_f32 v[80:81], v[88:89], v[80:81]
	v_pk_mul_f32 v[88:89], v[66:67], v[90:91] op_sel_hi:[1,0]
	v_pk_fma_f32 v[88:89], v[64:65], v[94:95], v[88:89] op_sel_hi:[1,0,1]
	v_lshl_add_u64 v[78:79], v[78:79], 0, s[6:7]
	v_pk_add_f32 v[80:81], v[88:89], v[80:81]
	v_pk_mul_f32 v[88:89], v[62:63], v[100:101] op_sel_hi:[1,0]
	s_waitcnt vmcnt(15)
	v_mov_b64_e32 v[90:91], v[184:185]
	v_mov_b64_e32 v[92:93], v[186:187]
	global_load_dwordx4 v[184:187], v[194:195], off offset:1024
	v_and_b32_e32 v100, 0xffff0000, v90
	v_pk_fma_f32 v[88:89], v[60:61], v[98:99], v[88:89] op_sel_hi:[1,0,1]
	v_lshlrev_b32_e32 v98, 16, v90
	v_and_b32_e32 v96, 0xffff0000, v91
	v_pk_mul_f32 v[74:75], v[74:75], v[100:101] op_sel_hi:[1,0]
	v_lshlrev_b32_e32 v94, 16, v91
	v_lshlrev_b32_e32 v90, 16, v92
	v_and_b32_e32 v92, 0xffff0000, v92
	v_pk_fma_f32 v[72:73], v[72:73], v[98:99], v[74:75] op_sel_hi:[1,0,1]
	v_pk_mul_f32 v[70:71], v[70:71], v[96:97] op_sel_hi:[1,0]
	v_pk_add_f32 v[80:81], v[88:89], v[80:81]
	v_and_b32_e32 v88, 0xffff0000, v93
	v_pk_add_f32 v[72:73], v[86:87], v[72:73]
	v_pk_fma_f32 v[68:69], v[68:69], v[94:95], v[70:71] op_sel_hi:[1,0,1]
	v_pk_mul_f32 v[66:67], v[66:67], v[92:93] op_sel_hi:[1,0]
	v_lshlrev_b32_e32 v2, 16, v93
	v_pk_add_f32 v[68:69], v[68:69], v[72:73]
	v_pk_fma_f32 v[64:65], v[64:65], v[90:91], v[66:67] op_sel_hi:[1,0,1]
	v_pk_mul_f32 v[62:63], v[62:63], v[88:89] op_sel_hi:[1,0]
	v_pk_add_f32 v[64:65], v[64:65], v[68:69]
	v_pk_fma_f32 v[60:61], v[60:61], v[2:3], v[62:63] op_sel_hi:[1,0,1]
	s_nop 0
	v_pk_add_f32 v[86:87], v[60:61], v[64:65]
	s_mov_b32 s5, 0xfffd0000
	v_add_co_u32_e32 v88, vcc, s5, v78
	v_add_u32_e32 v2, s4, v104
	s_nop 0
	v_addc_co_u32_e32 v89, vcc, -1, v79, vcc
	v_add_u32_e32 v60, 0x11000, v2
	ds_read_b128 v[72:75], v60
	v_add_u32_e32 v60, 0x11010, v2
	ds_read_b128 v[68:71], v60
	v_add_u32_e32 v60, 0x11020, v2
	ds_read_b128 v[64:67], v60
	v_add_u32_e32 v60, 0x11030, v2
	ds_read_b128 v[60:63], v60
	s_mov_b32 s5, 0xfffe0000
	s_addk_i32 s4, 0x1000
	s_mov_b64 s[6:7], 0x400
	s_cmpk_eq_i32 s4, 0x2000
	s_waitcnt vmcnt(15)
	v_mov_b64_e32 v[90:91], v[114:115]
	v_mov_b64_e32 v[92:93], v[116:117]
	v_lshlrev_b32_e32 v94, 16, v90
	v_and_b32_e32 v90, 0xffff0000, v90
	v_lshlrev_b32_e32 v96, 16, v91
	v_and_b32_e32 v98, 0xffff0000, v91
	s_waitcnt lgkmcnt(3)
	v_pk_mul_f32 v[90:91], v[74:75], v[90:91] op_sel_hi:[1,0]
	v_lshlrev_b32_e32 v100, 16, v92
	v_pk_fma_f32 v[90:91], v[72:73], v[94:95], v[90:91] op_sel_hi:[1,0,1]
	v_and_b32_e32 v92, 0xffff0000, v92
	v_pk_add_f32 v[84:85], v[84:85], v[90:91]
	s_waitcnt lgkmcnt(2)
	v_pk_mul_f32 v[90:91], v[70:71], v[98:99] op_sel_hi:[1,0]
	v_and_b32_e32 v108, 0xffff0000, v93
	v_pk_fma_f32 v[90:91], v[68:69], v[96:97], v[90:91] op_sel_hi:[1,0,1]
	v_lshlrev_b32_e32 v106, 16, v93
	v_pk_add_f32 v[84:85], v[90:91], v[84:85]
	s_waitcnt lgkmcnt(1)
	v_pk_mul_f32 v[90:91], v[66:67], v[92:93] op_sel_hi:[1,0]
	s_nop 0
	v_pk_fma_f32 v[90:91], v[64:65], v[100:101], v[90:91] op_sel_hi:[1,0,1]
	s_nop 0
	v_pk_add_f32 v[84:85], v[90:91], v[84:85]
	s_waitcnt lgkmcnt(0)
	v_pk_mul_f32 v[90:91], v[62:63], v[108:109] op_sel_hi:[1,0]
	s_nop 0
	v_pk_fma_f32 v[90:91], v[60:61], v[106:107], v[90:91] op_sel_hi:[1,0,1]
	s_nop 0
	v_pk_add_f32 v[84:85], v[90:91], v[84:85]
	v_add_co_u32_e32 v90, vcc, s5, v78
	s_nop 1
	v_addc_co_u32_e32 v91, vcc, -1, v79, vcc
	s_waitcnt vmcnt(14)
	v_mov_b64_e32 v[92:93], v[118:119]
	v_mov_b64_e32 v[94:95], v[120:121]
	v_lshlrev_b32_e32 v96, 16, v92
	v_and_b32_e32 v92, 0xffff0000, v92
	v_lshlrev_b32_e32 v98, 16, v93
	v_and_b32_e32 v100, 0xffff0000, v93
	v_pk_mul_f32 v[92:93], v[74:75], v[92:93] op_sel_hi:[1,0]
	v_lshlrev_b32_e32 v106, 16, v94
	v_pk_fma_f32 v[92:93], v[72:73], v[96:97], v[92:93] op_sel_hi:[1,0,1]
	v_and_b32_e32 v94, 0xffff0000, v94
	v_pk_add_f32 v[82:83], v[82:83], v[92:93]
	v_pk_mul_f32 v[92:93], v[70:71], v[100:101] op_sel_hi:[1,0]
	v_and_b32_e32 v110, 0xffff0000, v95
	v_pk_fma_f32 v[92:93], v[68:69], v[98:99], v[92:93] op_sel_hi:[1,0,1]
	v_lshlrev_b32_e32 v108, 16, v95
	v_pk_add_f32 v[82:83], v[92:93], v[82:83]
	v_pk_mul_f32 v[92:93], v[66:67], v[94:95] op_sel_hi:[1,0]
	s_nop 0
	v_pk_fma_f32 v[92:93], v[64:65], v[106:107], v[92:93] op_sel_hi:[1,0,1]
	s_nop 0
	v_pk_add_f32 v[82:83], v[92:93], v[82:83]
	v_pk_mul_f32 v[92:93], v[62:63], v[110:111] op_sel_hi:[1,0]
	s_nop 0
	v_pk_fma_f32 v[92:93], v[60:61], v[108:109], v[92:93] op_sel_hi:[1,0,1]
	s_nop 0
	v_pk_add_f32 v[94:95], v[92:93], v[82:83]
	v_add_co_u32_e32 v92, vcc, s33, v78
	s_nop 1
	v_addc_co_u32_e32 v93, vcc, -1, v79, vcc
	s_waitcnt vmcnt(13)
	v_mov_b64_e32 v[106:107], v[122:123]
	v_mov_b64_e32 v[108:109], v[124:125]
	v_and_b32_e32 v96, 0xffff0000, v106
	v_lshlrev_b32_e32 v82, 16, v106
	v_pk_mul_f32 v[96:97], v[74:75], v[96:97] op_sel_hi:[1,0]
	v_and_b32_e32 v100, 0xffff0000, v107
	v_pk_fma_f32 v[82:83], v[72:73], v[82:83], v[96:97] op_sel_hi:[1,0,1]
	v_lshlrev_b32_e32 v98, 16, v107
	v_pk_add_f32 v[80:81], v[80:81], v[82:83]
	v_pk_mul_f32 v[82:83], v[70:71], v[100:101] op_sel_hi:[1,0]
	v_lshlrev_b32_e32 v106, 16, v108
	v_and_b32_e32 v108, 0xffff0000, v108
	v_pk_fma_f32 v[82:83], v[68:69], v[98:99], v[82:83] op_sel_hi:[1,0,1]
	v_and_b32_e32 v112, 0xffff0000, v109
	v_pk_add_f32 v[80:81], v[82:83], v[80:81]
	v_pk_mul_f32 v[82:83], v[66:67], v[108:109] op_sel_hi:[1,0]
	v_lshlrev_b32_e32 v110, 16, v109
	v_pk_fma_f32 v[82:83], v[64:65], v[106:107], v[82:83] op_sel_hi:[1,0,1]
	s_nop 0
	v_pk_add_f32 v[80:81], v[82:83], v[80:81]
	v_pk_mul_f32 v[82:83], v[62:63], v[112:113] op_sel_hi:[1,0]
	s_nop 0
	v_pk_fma_f32 v[82:83], v[60:61], v[110:111], v[82:83] op_sel_hi:[1,0,1]
	s_nop 0
	v_pk_add_f32 v[96:97], v[82:83], v[80:81]
	s_waitcnt vmcnt(12)
	v_mov_b64_e32 v[80:81], v[126:127]
	v_mov_b64_e32 v[82:83], v[128:129]
	v_lshlrev_b32_e32 v108, 16, v82
	v_and_b32_e32 v82, 0xffff0000, v82
	v_and_b32_e32 v106, 0xffff0000, v81
	v_pk_mul_f32 v[66:67], v[66:67], v[82:83] op_sel_hi:[1,0]
	v_pk_mul_f32 v[70:71], v[70:71], v[106:107] op_sel_hi:[1,0]
	v_pk_fma_f32 v[64:65], v[64:65], v[108:109], v[66:67] op_sel_hi:[1,0,1]
	v_lshlrev_b32_e32 v98, 16, v80
	v_and_b32_e32 v80, 0xffff0000, v80
	v_pk_mul_f32 v[74:75], v[74:75], v[80:81] op_sel_hi:[1,0]
	v_lshlrev_b32_e32 v100, 16, v81
	v_pk_fma_f32 v[72:73], v[72:73], v[98:99], v[74:75] op_sel_hi:[1,0,1]
	v_and_b32_e32 v112, 0xffff0000, v83
	v_pk_add_f32 v[72:73], v[86:87], v[72:73]
	v_pk_fma_f32 v[68:69], v[68:69], v[100:101], v[70:71] op_sel_hi:[1,0,1]
	v_lshlrev_b32_e32 v110, 16, v83
	v_pk_add_f32 v[68:69], v[68:69], v[72:73]
	v_pk_mul_f32 v[62:63], v[62:63], v[112:113] op_sel_hi:[1,0]
	v_pk_add_f32 v[64:65], v[64:65], v[68:69]
	v_pk_fma_f32 v[60:61], v[60:61], v[110:111], v[62:63] op_sel_hi:[1,0,1]
	s_waitcnt vmcnt(11)
	v_mov_b64_e32 v[106:107], v[130:131]
	v_mov_b64_e32 v[108:109], v[132:133]
	v_and_b32_e32 v86, 0xffff0000, v106
	v_pk_add_f32 v[80:81], v[60:61], v[64:65]
	v_add_u32_e32 v60, 0x11400, v2
	ds_read_b128 v[72:75], v60
	v_add_u32_e32 v60, 0x11410, v2
	ds_read_b128 v[68:71], v60
	v_add_u32_e32 v60, 0x11420, v2
	ds_read_b128 v[64:67], v60
	v_add_u32_e32 v60, 0x11430, v2
	v_lshlrev_b32_e32 v82, 16, v106
	s_waitcnt lgkmcnt(2)
	v_pk_mul_f32 v[86:87], v[74:75], v[86:87] op_sel_hi:[1,0]
	ds_read_b128 v[60:63], v60
	v_and_b32_e32 v100, 0xffff0000, v107
	v_pk_fma_f32 v[82:83], v[72:73], v[82:83], v[86:87] op_sel_hi:[1,0,1]
	v_lshlrev_b32_e32 v98, 16, v107
	v_pk_add_f32 v[82:83], v[84:85], v[82:83]
	s_waitcnt lgkmcnt(2)
	v_pk_mul_f32 v[84:85], v[70:71], v[100:101] op_sel_hi:[1,0]
	v_lshlrev_b32_e32 v106, 16, v108
	v_and_b32_e32 v108, 0xffff0000, v108
	v_pk_fma_f32 v[84:85], v[68:69], v[98:99], v[84:85] op_sel_hi:[1,0,1]
	v_and_b32_e32 v112, 0xffff0000, v109
	v_pk_add_f32 v[82:83], v[84:85], v[82:83]
	s_waitcnt lgkmcnt(1)
	v_pk_mul_f32 v[84:85], v[66:67], v[108:109] op_sel_hi:[1,0]
	v_lshlrev_b32_e32 v110, 16, v109
	v_pk_fma_f32 v[84:85], v[64:65], v[106:107], v[84:85] op_sel_hi:[1,0,1]
	s_nop 0
	v_pk_add_f32 v[82:83], v[84:85], v[82:83]
	s_waitcnt lgkmcnt(0)
	v_pk_mul_f32 v[84:85], v[62:63], v[112:113] op_sel_hi:[1,0]
	s_nop 0
	v_pk_fma_f32 v[84:85], v[60:61], v[110:111], v[84:85] op_sel_hi:[1,0,1]
	s_nop 0
	v_pk_add_f32 v[82:83], v[84:85], v[82:83]
	s_waitcnt vmcnt(10)
	v_mov_b64_e32 v[84:85], v[134:135]
	v_mov_b64_e32 v[86:87], v[136:137]
	v_lshlrev_b32_e32 v98, 16, v84
	v_and_b32_e32 v84, 0xffff0000, v84
	v_lshlrev_b32_e32 v100, 16, v85
	v_and_b32_e32 v106, 0xffff0000, v85
	v_lshlrev_b32_e32 v108, 16, v86
	v_and_b32_e32 v86, 0xffff0000, v86
	v_pk_mul_f32 v[84:85], v[74:75], v[84:85] op_sel_hi:[1,0]
	v_lshlrev_b32_e32 v110, 16, v87
	v_and_b32_e32 v112, 0xffff0000, v87
	v_pk_fma_f32 v[84:85], v[72:73], v[98:99], v[84:85] op_sel_hi:[1,0,1]
	v_pk_mul_f32 v[86:87], v[66:67], v[86:87] op_sel_hi:[1,0]
	v_pk_add_f32 v[84:85], v[94:95], v[84:85]
	v_pk_mul_f32 v[94:95], v[70:71], v[106:107] op_sel_hi:[1,0]
	v_pk_fma_f32 v[86:87], v[64:65], v[108:109], v[86:87] op_sel_hi:[1,0,1]
	v_pk_fma_f32 v[94:95], v[68:69], v[100:101], v[94:95] op_sel_hi:[1,0,1]
	s_waitcnt vmcnt(9)
	v_mov_b64_e32 v[106:107], v[138:139]
	v_mov_b64_e32 v[108:109], v[140:141]
	v_and_b32_e32 v100, 0xffff0000, v107
	v_pk_add_f32 v[84:85], v[94:95], v[84:85]
	v_and_b32_e32 v94, 0xffff0000, v106
	v_pk_add_f32 v[84:85], v[86:87], v[84:85]
	v_pk_mul_f32 v[86:87], v[62:63], v[112:113] op_sel_hi:[1,0]
	v_pk_mul_f32 v[94:95], v[74:75], v[94:95] op_sel_hi:[1,0]
	v_pk_fma_f32 v[86:87], v[60:61], v[110:111], v[86:87] op_sel_hi:[1,0,1]
	v_lshlrev_b32_e32 v98, 16, v107
	v_pk_add_f32 v[84:85], v[86:87], v[84:85]
	v_lshlrev_b32_e32 v86, 16, v106
	v_pk_fma_f32 v[86:87], v[72:73], v[86:87], v[94:95] op_sel_hi:[1,0,1]
	v_pk_mul_f32 v[94:95], v[70:71], v[100:101] op_sel_hi:[1,0]
	v_lshlrev_b32_e32 v106, 16, v108
	v_and_b32_e32 v108, 0xffff0000, v108
	v_pk_add_f32 v[86:87], v[96:97], v[86:87]
	v_pk_fma_f32 v[94:95], v[68:69], v[98:99], v[94:95] op_sel_hi:[1,0,1]
	v_and_b32_e32 v112, 0xffff0000, v109
	v_pk_add_f32 v[86:87], v[94:95], v[86:87]
	v_pk_mul_f32 v[94:95], v[66:67], v[108:109] op_sel_hi:[1,0]
	v_lshlrev_b32_e32 v110, 16, v109
	v_pk_fma_f32 v[94:95], v[64:65], v[106:107], v[94:95] op_sel_hi:[1,0,1]
	s_nop 0
	v_pk_add_f32 v[86:87], v[94:95], v[86:87]
	v_pk_mul_f32 v[94:95], v[62:63], v[112:113] op_sel_hi:[1,0]
	s_nop 0
	v_pk_fma_f32 v[94:95], v[60:61], v[110:111], v[94:95] op_sel_hi:[1,0,1]
	s_nop 0
	v_pk_add_f32 v[86:87], v[94:95], v[86:87]
	s_waitcnt vmcnt(8)
	v_mov_b64_e32 v[94:95], v[142:143]
	v_mov_b64_e32 v[96:97], v[144:145]
	v_lshlrev_b32_e32 v98, 16, v94
	v_and_b32_e32 v94, 0xffff0000, v94
	v_lshlrev_b32_e32 v108, 16, v96
	v_and_b32_e32 v96, 0xffff0000, v96
	v_lshlrev_b32_e32 v100, 16, v95
	v_and_b32_e32 v106, 0xffff0000, v95
	v_lshlrev_b32_e32 v110, 16, v97
	v_and_b32_e32 v112, 0xffff0000, v97
	v_pk_mul_f32 v[74:75], v[74:75], v[94:95] op_sel_hi:[1,0]
	v_pk_mul_f32 v[66:67], v[66:67], v[96:97] op_sel_hi:[1,0]
	v_pk_fma_f32 v[72:73], v[72:73], v[98:99], v[74:75] op_sel_hi:[1,0,1]
	v_pk_mul_f32 v[70:71], v[70:71], v[106:107] op_sel_hi:[1,0]
	v_pk_add_f32 v[72:73], v[80:81], v[72:73]
	v_pk_fma_f32 v[68:69], v[68:69], v[100:101], v[70:71] op_sel_hi:[1,0,1]
	v_pk_fma_f32 v[64:65], v[64:65], v[108:109], v[66:67] op_sel_hi:[1,0,1]
	v_pk_add_f32 v[68:69], v[68:69], v[72:73]
	v_pk_mul_f32 v[62:63], v[62:63], v[112:113] op_sel_hi:[1,0]
	v_pk_add_f32 v[64:65], v[64:65], v[68:69]
	v_pk_fma_f32 v[60:61], v[60:61], v[110:111], v[62:63] op_sel_hi:[1,0,1]
	s_waitcnt vmcnt(7)
	v_mov_b64_e32 v[94:95], v[146:147]
	v_mov_b64_e32 v[96:97], v[148:149]
	v_lshlrev_b32_e32 v98, 16, v94
	v_pk_add_f32 v[80:81], v[60:61], v[64:65]
	v_add_u32_e32 v60, 0x11800, v2
	ds_read_b128 v[72:75], v60
	v_add_u32_e32 v60, 0x11810, v2
	ds_read_b128 v[68:71], v60
	v_add_u32_e32 v60, 0x11820, v2
	ds_read_b128 v[64:67], v60
	v_and_b32_e32 v94, 0xffff0000, v94
	v_add_u32_e32 v60, 0x11830, v2
	v_lshlrev_b32_e32 v100, 16, v95
	v_and_b32_e32 v106, 0xffff0000, v95
	s_waitcnt lgkmcnt(2)
	v_pk_mul_f32 v[94:95], v[74:75], v[94:95] op_sel_hi:[1,0]
	ds_read_b128 v[60:63], v60
	v_pk_fma_f32 v[94:95], v[72:73], v[98:99], v[94:95] op_sel_hi:[1,0,1]
	v_lshlrev_b32_e32 v108, 16, v96
	v_pk_add_f32 v[82:83], v[82:83], v[94:95]
	s_waitcnt lgkmcnt(2)
	v_pk_mul_f32 v[94:95], v[70:71], v[106:107] op_sel_hi:[1,0]
	v_and_b32_e32 v96, 0xffff0000, v96
	v_pk_fma_f32 v[94:95], v[68:69], v[100:101], v[94:95] op_sel_hi:[1,0,1]
	v_and_b32_e32 v112, 0xffff0000, v97
	v_pk_add_f32 v[82:83], v[94:95], v[82:83]
	s_waitcnt lgkmcnt(1)
	v_pk_mul_f32 v[94:95], v[66:67], v[96:97] op_sel_hi:[1,0]
	v_lshlrev_b32_e32 v110, 16, v97
	v_pk_fma_f32 v[94:95], v[64:65], v[108:109], v[94:95] op_sel_hi:[1,0,1]
	s_nop 0
	v_pk_add_f32 v[82:83], v[94:95], v[82:83]
	s_waitcnt lgkmcnt(0)
	v_pk_mul_f32 v[94:95], v[62:63], v[112:113] op_sel_hi:[1,0]
	s_nop 0
	v_pk_fma_f32 v[94:95], v[60:61], v[110:111], v[94:95] op_sel_hi:[1,0,1]
	s_nop 0
	v_pk_add_f32 v[82:83], v[94:95], v[82:83]
	s_waitcnt vmcnt(6)
	v_mov_b64_e32 v[94:95], v[150:151]
	v_mov_b64_e32 v[96:97], v[152:153]
	v_lshlrev_b32_e32 v98, 16, v94
	v_and_b32_e32 v94, 0xffff0000, v94
	v_lshlrev_b32_e32 v100, 16, v95
	v_and_b32_e32 v106, 0xffff0000, v95
	v_pk_mul_f32 v[94:95], v[74:75], v[94:95] op_sel_hi:[1,0]
	v_lshlrev_b32_e32 v108, 16, v96
	v_pk_fma_f32 v[94:95], v[72:73], v[98:99], v[94:95] op_sel_hi:[1,0,1]
	v_and_b32_e32 v96, 0xffff0000, v96
	v_pk_add_f32 v[84:85], v[84:85], v[94:95]
	v_pk_mul_f32 v[94:95], v[70:71], v[106:107] op_sel_hi:[1,0]
	v_and_b32_e32 v112, 0xffff0000, v97
	v_pk_fma_f32 v[94:95], v[68:69], v[100:101], v[94:95] op_sel_hi:[1,0,1]
	v_lshlrev_b32_e32 v110, 16, v97
	v_pk_add_f32 v[84:85], v[94:95], v[84:85]
	v_pk_mul_f32 v[94:95], v[66:67], v[96:97] op_sel_hi:[1,0]
	s_nop 0
	v_pk_fma_f32 v[94:95], v[64:65], v[108:109], v[94:95] op_sel_hi:[1,0,1]
	v_pk_add_f32 v[84:85], v[94:95], v[84:85]
	v_pk_mul_f32 v[94:95], v[62:63], v[112:113] op_sel_hi:[1,0]
	s_waitcnt vmcnt(5)
	v_mov_b64_e32 v[106:107], v[154:155]
	v_mov_b64_e32 v[108:109], v[156:157]
	v_and_b32_e32 v96, 0xffff0000, v106
	v_pk_fma_f32 v[94:95], v[60:61], v[110:111], v[94:95] op_sel_hi:[1,0,1]
	v_pk_mul_f32 v[96:97], v[74:75], v[96:97] op_sel_hi:[1,0]
	v_pk_add_f32 v[94:95], v[94:95], v[84:85]
	v_lshlrev_b32_e32 v84, 16, v106
	v_and_b32_e32 v100, 0xffff0000, v107
	v_pk_fma_f32 v[84:85], v[72:73], v[84:85], v[96:97] op_sel_hi:[1,0,1]
	v_lshlrev_b32_e32 v98, 16, v107
	v_pk_add_f32 v[84:85], v[86:87], v[84:85]
	v_pk_mul_f32 v[86:87], v[70:71], v[100:101] op_sel_hi:[1,0]
	v_lshlrev_b32_e32 v106, 16, v108
	v_and_b32_e32 v108, 0xffff0000, v108
	v_pk_fma_f32 v[86:87], v[68:69], v[98:99], v[86:87] op_sel_hi:[1,0,1]
	v_and_b32_e32 v112, 0xffff0000, v109
	v_pk_add_f32 v[84:85], v[86:87], v[84:85]
	v_pk_mul_f32 v[86:87], v[66:67], v[108:109] op_sel_hi:[1,0]
	v_lshlrev_b32_e32 v110, 16, v109
	v_pk_fma_f32 v[86:87], v[64:65], v[106:107], v[86:87] op_sel_hi:[1,0,1]
	s_nop 0
	v_pk_add_f32 v[84:85], v[86:87], v[84:85]
	v_pk_mul_f32 v[86:87], v[62:63], v[112:113] op_sel_hi:[1,0]
	s_nop 0
	v_pk_fma_f32 v[86:87], v[60:61], v[110:111], v[86:87] op_sel_hi:[1,0,1]
	s_nop 0
	v_pk_add_f32 v[96:97], v[86:87], v[84:85]
	s_waitcnt vmcnt(4)
	v_mov_b64_e32 v[84:85], v[158:159]
	v_mov_b64_e32 v[86:87], v[160:161]
	v_lshlrev_b32_e32 v108, 16, v86
	v_and_b32_e32 v86, 0xffff0000, v86
	v_and_b32_e32 v106, 0xffff0000, v85
	v_pk_mul_f32 v[66:67], v[66:67], v[86:87] op_sel_hi:[1,0]
	v_pk_mul_f32 v[70:71], v[70:71], v[106:107] op_sel_hi:[1,0]
	v_pk_fma_f32 v[64:65], v[64:65], v[108:109], v[66:67] op_sel_hi:[1,0,1]
	v_lshlrev_b32_e32 v98, 16, v84
	v_and_b32_e32 v84, 0xffff0000, v84
	v_pk_mul_f32 v[74:75], v[74:75], v[84:85] op_sel_hi:[1,0]
	v_lshlrev_b32_e32 v100, 16, v85
	v_pk_fma_f32 v[72:73], v[72:73], v[98:99], v[74:75] op_sel_hi:[1,0,1]
	v_and_b32_e32 v112, 0xffff0000, v87
	v_pk_add_f32 v[72:73], v[80:81], v[72:73]
	v_pk_fma_f32 v[68:69], v[68:69], v[100:101], v[70:71] op_sel_hi:[1,0,1]
	v_lshlrev_b32_e32 v110, 16, v87
	v_pk_add_f32 v[68:69], v[68:69], v[72:73]
	v_pk_mul_f32 v[62:63], v[62:63], v[112:113] op_sel_hi:[1,0]
	v_pk_add_f32 v[64:65], v[64:65], v[68:69]
	v_pk_fma_f32 v[60:61], v[60:61], v[110:111], v[62:63] op_sel_hi:[1,0,1]
	s_waitcnt vmcnt(3)
	v_mov_b64_e32 v[106:107], v[162:163]
	v_mov_b64_e32 v[108:109], v[164:165]
	v_and_b32_e32 v80, 0xffff0000, v106
	v_pk_add_f32 v[86:87], v[60:61], v[64:65]
	v_add_u32_e32 v60, 0x11c00, v2
	ds_read_b128 v[72:75], v60
	v_add_u32_e32 v60, 0x11c10, v2
	ds_read_b128 v[68:71], v60
	v_add_u32_e32 v60, 0x11c20, v2
	ds_read_b128 v[64:67], v60
	v_add_u32_e32 v2, 0x11c30, v2
	ds_read_b128 v[60:63], v2
	v_lshlrev_b32_e32 v2, 16, v106
	s_waitcnt lgkmcnt(3)
	v_pk_mul_f32 v[80:81], v[74:75], v[80:81] op_sel_hi:[1,0]
	v_and_b32_e32 v88, 0xffff0000, v107
	v_pk_fma_f32 v[80:81], v[72:73], v[2:3], v[80:81] op_sel_hi:[1,0,1]
	v_lshlrev_b32_e32 v84, 16, v107
	v_pk_add_f32 v[80:81], v[82:83], v[80:81]
	s_waitcnt lgkmcnt(2)
	v_pk_mul_f32 v[82:83], v[70:71], v[88:89] op_sel_hi:[1,0]
	v_and_b32_e32 v100, 0xffff0000, v108
	v_pk_fma_f32 v[82:83], v[68:69], v[84:85], v[82:83] op_sel_hi:[1,0,1]
	v_lshlrev_b32_e32 v98, 16, v108
	v_pk_add_f32 v[80:81], v[82:83], v[80:81]
	s_waitcnt lgkmcnt(1)
	v_pk_mul_f32 v[82:83], v[66:67], v[100:101] op_sel_hi:[1,0]
	v_and_b32_e32 v108, 0xffff0000, v109
	v_pk_fma_f32 v[82:83], v[64:65], v[98:99], v[82:83] op_sel_hi:[1,0,1]
	v_lshlrev_b32_e32 v106, 16, v109
	v_pk_add_f32 v[80:81], v[82:83], v[80:81]
	s_waitcnt lgkmcnt(0)
	v_pk_mul_f32 v[82:83], v[62:63], v[108:109] op_sel_hi:[1,0]
	s_nop 0
	v_pk_fma_f32 v[82:83], v[60:61], v[106:107], v[82:83] op_sel_hi:[1,0,1]
	s_nop 0
	v_pk_add_f32 v[84:85], v[82:83], v[80:81]
	s_waitcnt vmcnt(2)
	v_mov_b64_e32 v[80:81], v[176:177]
	v_mov_b64_e32 v[82:83], v[178:179]
	v_lshlrev_b32_e32 v2, 16, v80
	v_and_b32_e32 v80, 0xffff0000, v80
	v_lshlrev_b32_e32 v88, 16, v81
	v_and_b32_e32 v90, 0xffff0000, v81
	v_pk_mul_f32 v[80:81], v[74:75], v[80:81] op_sel_hi:[1,0]
	v_pk_mul_f32 v[90:91], v[70:71], v[90:91] op_sel_hi:[1,0]
	v_pk_fma_f32 v[80:81], v[72:73], v[2:3], v[80:81] op_sel_hi:[1,0,1]
	v_pk_fma_f32 v[88:89], v[68:69], v[88:89], v[90:91] op_sel_hi:[1,0,1]
	v_pk_add_f32 v[80:81], v[94:95], v[80:81]
	v_lshlrev_b32_e32 v98, 16, v82
	v_pk_add_f32 v[80:81], v[88:89], v[80:81]
	v_and_b32_e32 v82, 0xffff0000, v82
	v_lshlrev_b32_e32 v100, 16, v83
	v_and_b32_e32 v106, 0xffff0000, v83
	v_pk_mul_f32 v[82:83], v[66:67], v[82:83] op_sel_hi:[1,0]
	s_waitcnt vmcnt(1)
	v_mov_b64_e32 v[88:89], v[180:181]
	v_mov_b64_e32 v[90:91], v[182:183]
	v_lshlrev_b32_e32 v2, 16, v88
	v_pk_fma_f32 v[82:83], v[64:65], v[98:99], v[82:83] op_sel_hi:[1,0,1]
	v_and_b32_e32 v92, 0xffff0000, v89
	v_pk_add_f32 v[80:81], v[82:83], v[80:81]
	v_pk_mul_f32 v[82:83], v[62:63], v[106:107] op_sel_hi:[1,0]
	v_pk_mul_f32 v[92:93], v[70:71], v[92:93] op_sel_hi:[1,0]
	v_pk_fma_f32 v[82:83], v[60:61], v[100:101], v[82:83] op_sel_hi:[1,0,1]
	v_lshlrev_b32_e32 v94, 16, v90
	v_pk_add_f32 v[82:83], v[82:83], v[80:81]
	v_and_b32_e32 v80, 0xffff0000, v88
	v_pk_mul_f32 v[80:81], v[74:75], v[80:81] op_sel_hi:[1,0]
	v_lshlrev_b32_e32 v88, 16, v89
	v_pk_fma_f32 v[80:81], v[72:73], v[2:3], v[80:81] op_sel_hi:[1,0,1]
	v_and_b32_e32 v90, 0xffff0000, v90
	v_pk_add_f32 v[80:81], v[96:97], v[80:81]
	v_pk_fma_f32 v[88:89], v[68:69], v[88:89], v[92:93] op_sel_hi:[1,0,1]
	v_lshlrev_b32_e32 v98, 16, v91
	v_and_b32_e32 v100, 0xffff0000, v91
	v_pk_add_f32 v[80:81], v[88:89], v[80:81]
	v_pk_mul_f32 v[88:89], v[66:67], v[90:91] op_sel_hi:[1,0]
	v_pk_fma_f32 v[88:89], v[64:65], v[94:95], v[88:89] op_sel_hi:[1,0,1]
	v_lshl_add_u64 v[78:79], v[78:79], 0, s[6:7]
	v_pk_add_f32 v[80:81], v[88:89], v[80:81]
	v_pk_mul_f32 v[88:89], v[62:63], v[100:101] op_sel_hi:[1,0]
	s_waitcnt vmcnt(0)
	s_add_u32 s56, s28, s22
	s_addc_u32 s57, s29, s23
	s_add_u32 s56, s56, 0x10000
	s_addc_u32 s57, s57, 0
	v_add_u32_e32 v124, s63, v102
	v_ashrrev_i32_e32 v125, 31, v124
	v_lshlrev_b64 v[124:125], 4, v[124:125]
	v_lshl_add_u64 v[124:125], s[56:57], 0, v[124:125]
	global_load_dwordx4 v[108:111], v[124:125], off
	global_load_dwordx4 v[112:115], v[124:125], off offset:512
	global_load_dwordx4 v[116:119], v[124:125], off offset:1024
	global_load_dwordx4 v[120:123], v[124:125], off offset:1536
	v_mov_b64_e32 v[90:91], v[184:185]
	v_mov_b64_e32 v[92:93], v[186:187]
	v_and_b32_e32 v100, 0xffff0000, v90
	v_pk_fma_f32 v[88:89], v[60:61], v[98:99], v[88:89] op_sel_hi:[1,0,1]
	v_lshlrev_b32_e32 v98, 16, v90
	v_and_b32_e32 v96, 0xffff0000, v91
	v_pk_mul_f32 v[74:75], v[74:75], v[100:101] op_sel_hi:[1,0]
	v_lshlrev_b32_e32 v94, 16, v91
	v_lshlrev_b32_e32 v90, 16, v92
	v_and_b32_e32 v92, 0xffff0000, v92
	v_pk_fma_f32 v[72:73], v[72:73], v[98:99], v[74:75] op_sel_hi:[1,0,1]
	v_pk_mul_f32 v[70:71], v[70:71], v[96:97] op_sel_hi:[1,0]
	v_pk_add_f32 v[80:81], v[88:89], v[80:81]
	v_and_b32_e32 v88, 0xffff0000, v93
	v_pk_add_f32 v[72:73], v[86:87], v[72:73]
	v_pk_fma_f32 v[68:69], v[68:69], v[94:95], v[70:71] op_sel_hi:[1,0,1]
	v_pk_mul_f32 v[66:67], v[66:67], v[92:93] op_sel_hi:[1,0]
	v_lshlrev_b32_e32 v2, 16, v93
	v_pk_add_f32 v[68:69], v[68:69], v[72:73]
	v_pk_fma_f32 v[64:65], v[64:65], v[90:91], v[66:67] op_sel_hi:[1,0,1]
	v_pk_mul_f32 v[62:63], v[62:63], v[88:89] op_sel_hi:[1,0]
	v_pk_add_f32 v[64:65], v[64:65], v[68:69]
	v_pk_fma_f32 v[60:61], v[60:61], v[2:3], v[62:63] op_sel_hi:[1,0,1]
	s_nop 0
	v_pk_add_f32 v[86:87], v[60:61], v[64:65]
	v_and_b32_e32 v64, 64, v218
	v_add_u32_e32 v67, 64, v64
	v_xor_b32_e32 v2, 1, v218
	v_cmp_lt_i32_e32 vcc, v2, v67
	v_xor_b32_e32 v62, 2, v218
	v_xor_b32_e32 v66, 4, v218
	v_cndmask_b32_e32 v2, v218, v2, vcc
	v_lshlrev_b32_e32 v2, 2, v2
	ds_bpermute_b32 v60, v2, v84
	ds_bpermute_b32 v61, v2, v85
	v_cmp_lt_i32_e32 vcc, v62, v67
	s_add_u32 s4, s28, s22
	s_addc_u32 s5, s29, s23
	v_cndmask_b32_e32 v62, v218, v62, vcc
	v_lshlrev_b32_e32 v65, 2, v62
	s_waitcnt lgkmcnt(0)
	v_pk_add_f32 v[60:61], v[84:85], v[60:61]
	ds_bpermute_b32 v62, v65, v60
	ds_bpermute_b32 v63, v65, v61
	v_cmp_lt_i32_e32 vcc, v66, v67
	s_add_u32 s30, s4, 0x10000
	s_addc_u32 s31, s5, 0
	v_cndmask_b32_e32 v66, v218, v66, vcc
	v_lshlrev_b32_e32 v66, 2, v66
	s_waitcnt lgkmcnt(0)
	v_pk_add_f32 v[60:61], v[60:61], v[62:63]
	ds_bpermute_b32 v62, v66, v60
	ds_bpermute_b32 v63, v66, v61
	s_lshl_b32 s6, s34, 2
	s_add_u32 s6, s28, s6
	s_addc_u32 s7, s29, 0
	s_add_u32 s18, s6, 0x5200000
	s_waitcnt lgkmcnt(0)
	v_pk_add_f32 v[60:61], v[60:61], v[62:63]
	v_xor_b32_e32 v62, 8, v218
	v_cmp_lt_i32_e32 vcc, v62, v67
	v_cmp_eq_u32_e64 s[4:5], 0, v99
	s_addc_u32 s19, s7, 0
	v_cndmask_b32_e32 v62, v218, v62, vcc
	v_lshlrev_b32_e32 v67, 2, v62
	ds_bpermute_b32 v62, v67, v60
	ds_bpermute_b32 v63, v67, v61
	s_waitcnt vmcnt(0)
	s_and_saveexec_b64 s[40:41], s[4:5]
	s_cbranch_execz .LBB0_330
	v_add_u32_e32 v68, s63, v102
	v_ashrrev_i32_e32 v69, 31, v68
	v_lshlrev_b64 v[72:73], 4, v[68:69]
	v_lshl_add_u64 v[68:69], s[30:31], 0, v[72:73]
	s_mov_b32 s6, 0xf800000
	s_waitcnt lgkmcnt(0)
	v_pk_add_f32 v[60:61], v[60:61], v[62:63]
	v_mov_b64_e32 v[68:69], v[108:109]
	v_mov_b64_e32 v[70:71], v[110:111]
	v_mov_b32_e32 v74, v69
	v_mov_b32_e32 v75, v70
	v_mov_b32_e32 v69, v71
	v_pk_add_f32 v[68:69], v[74:75], v[68:69]
	v_lshl_add_u32 v70, v102, 3, 0
	v_add_f32_e32 v68, v68, v69
	v_fmamk_f32 v68, v68, 0x3a800000, v215
	v_mul_f32_e32 v69, 0x4f800000, v68
	v_cmp_gt_f32_e32 vcc, s6, v68
	v_add_u32_e32 v70, 0x22c00, v70
	s_nop 0
	v_cndmask_b32_e32 v68, v68, v69, vcc
	v_sqrt_f32_e32 v69, v68
	s_nop 0
	v_add_u32_e32 v62, -1, v69
	v_add_u32_e32 v63, 1, v69
	v_fma_f32 v71, -v62, v69, v68
	v_fma_f32 v74, -v63, v69, v68
	v_cmp_ge_f32_e64 s[6:7], 0, v71
	s_nop 1
	v_cndmask_b32_e64 v62, v69, v62, s[6:7]
	v_cmp_lt_f32_e64 s[6:7], 0, v74
	s_nop 1
	v_cndmask_b32_e64 v62, v62, v63, s[6:7]
	v_mul_f32_e32 v63, 0x37800000, v62
	v_cndmask_b32_e32 v62, v62, v63, vcc
	v_cmp_class_f32_e32 vcc, v68, v216
	s_nop 1
	v_cndmask_b32_e32 v68, v62, v68, vcc
	v_div_scale_f32 v69, s[6:7], v68, v68, 1.0
	v_rcp_f32_e32 v71, v69
	v_lshl_add_u64 v[62:63], s[18:19], 0, v[72:73]
	v_div_scale_f32 v72, vcc, 1.0, v68, 1.0
	v_fma_f32 v73, -v69, v71, 1.0
	v_fmac_f32_e32 v71, v73, v71
	v_mul_f32_e32 v73, v72, v71
	v_fma_f32 v74, -v69, v73, v72
	v_fmac_f32_e32 v73, v74, v71
	v_fma_f32 v69, -v69, v73, v72
	v_div_fmas_f32 v69, v69, v71, v73
	v_div_fixup_f32 v68, v69, v68, 1.0
	v_pk_mul_f32 v[60:61], v[60:61], v[68:69] op_sel_hi:[1,0]
	ds_write_b64 v70, v[60:61]
	global_store_dwordx2 v[62:63], v[60:61], off
.LBB0_330:
	s_or_b64 exec, exec, s[40:41]
	ds_bpermute_b32 v60, v2, v82
	ds_bpermute_b32 v61, v2, v83
	s_waitcnt lgkmcnt(0)
	v_pk_add_f32 v[60:61], v[82:83], v[60:61]
	ds_bpermute_b32 v62, v65, v60
	ds_bpermute_b32 v63, v65, v61
	s_waitcnt lgkmcnt(0)
	v_pk_add_f32 v[60:61], v[60:61], v[62:63]
	ds_bpermute_b32 v62, v66, v60
	ds_bpermute_b32 v63, v66, v61
	s_waitcnt lgkmcnt(0)
	v_pk_add_f32 v[60:61], v[60:61], v[62:63]
	ds_bpermute_b32 v62, v67, v60
	ds_bpermute_b32 v63, v67, v61
	s_and_saveexec_b64 s[40:41], s[4:5]
	s_cbranch_execz .LBB0_332
	v_add_u32_e32 v78, 32, v102
	v_add_u32_e32 v68, s63, v78
	v_ashrrev_i32_e32 v69, 31, v68
	v_lshlrev_b64 v[72:73], 4, v[68:69]
	v_lshl_add_u64 v[68:69], s[30:31], 0, v[72:73]
	s_mov_b32 s6, 0xf800000
	s_waitcnt lgkmcnt(0)
	v_pk_add_f32 v[60:61], v[60:61], v[62:63]
	v_lshl_add_u32 v62, v78, 3, 0
	v_mov_b64_e32 v[68:69], v[112:113]
	v_mov_b64_e32 v[70:71], v[114:115]
	v_mov_b32_e32 v74, v69
	v_mov_b32_e32 v75, v70
	v_mov_b32_e32 v69, v71
	v_pk_add_f32 v[68:69], v[74:75], v[68:69]
	v_add_u32_e32 v70, 0x22c00, v62
	v_add_f32_e32 v68, v68, v69
	v_fmamk_f32 v68, v68, 0x3a800000, v215
	v_mul_f32_e32 v69, 0x4f800000, v68
	v_cmp_gt_f32_e32 vcc, s6, v68
	s_nop 1
	v_cndmask_b32_e32 v68, v68, v69, vcc
	v_sqrt_f32_e32 v69, v68
	s_nop 0
	v_add_u32_e32 v62, -1, v69
	v_add_u32_e32 v63, 1, v69
	v_fma_f32 v71, -v62, v69, v68
	v_fma_f32 v74, -v63, v69, v68
	v_cmp_ge_f32_e64 s[6:7], 0, v71
	s_nop 1
	v_cndmask_b32_e64 v62, v69, v62, s[6:7]
	v_cmp_lt_f32_e64 s[6:7], 0, v74
	s_nop 1
	v_cndmask_b32_e64 v62, v62, v63, s[6:7]
	v_mul_f32_e32 v63, 0x37800000, v62
	v_cndmask_b32_e32 v62, v62, v63, vcc
	v_cmp_class_f32_e32 vcc, v68, v216
	s_nop 1
	v_cndmask_b32_e32 v68, v62, v68, vcc
	v_div_scale_f32 v69, s[6:7], v68, v68, 1.0
	v_rcp_f32_e32 v71, v69
	v_lshl_add_u64 v[62:63], s[18:19], 0, v[72:73]
	v_div_scale_f32 v72, vcc, 1.0, v68, 1.0
	v_fma_f32 v73, -v69, v71, 1.0
	v_fmac_f32_e32 v71, v73, v71
	v_mul_f32_e32 v73, v72, v71
	v_fma_f32 v74, -v69, v73, v72
	v_fmac_f32_e32 v73, v74, v71
	v_fma_f32 v69, -v69, v73, v72
	v_div_fmas_f32 v69, v69, v71, v73
	v_div_fixup_f32 v68, v69, v68, 1.0
	v_pk_mul_f32 v[60:61], v[60:61], v[68:69] op_sel_hi:[1,0]
	ds_write_b64 v70, v[60:61]
	global_store_dwordx2 v[62:63], v[60:61], off
.LBB0_332:
	s_or_b64 exec, exec, s[40:41]
	ds_bpermute_b32 v60, v2, v80
	ds_bpermute_b32 v61, v2, v81
	s_waitcnt lgkmcnt(0)
	v_pk_add_f32 v[60:61], v[80:81], v[60:61]
	ds_bpermute_b32 v62, v65, v60
	ds_bpermute_b32 v63, v65, v61
	s_waitcnt lgkmcnt(0)
	v_pk_add_f32 v[60:61], v[60:61], v[62:63]
	ds_bpermute_b32 v62, v66, v60
	ds_bpermute_b32 v63, v66, v61
	s_waitcnt lgkmcnt(0)
	v_pk_add_f32 v[60:61], v[60:61], v[62:63]
	ds_bpermute_b32 v62, v67, v60
	ds_bpermute_b32 v63, v67, v61
	s_and_saveexec_b64 s[40:41], s[4:5]
	s_cbranch_execz .LBB0_334
	v_add_u32_e32 v78, 64, v102
	v_add_u32_e32 v68, s63, v78
	v_ashrrev_i32_e32 v69, 31, v68
	v_lshlrev_b64 v[72:73], 4, v[68:69]
	v_lshl_add_u64 v[68:69], s[30:31], 0, v[72:73]
	s_mov_b32 s6, 0xf800000
	s_waitcnt lgkmcnt(0)
	v_pk_add_f32 v[60:61], v[60:61], v[62:63]
	v_lshl_add_u32 v62, v78, 3, 0
	v_mov_b64_e32 v[68:69], v[116:117]
	v_mov_b64_e32 v[70:71], v[118:119]
	v_mov_b32_e32 v74, v69
	v_mov_b32_e32 v75, v70
	v_mov_b32_e32 v69, v71
	v_pk_add_f32 v[68:69], v[74:75], v[68:69]
	v_add_u32_e32 v70, 0x22c00, v62
	v_add_f32_e32 v68, v68, v69
	v_fmamk_f32 v68, v68, 0x3a800000, v215
	v_mul_f32_e32 v69, 0x4f800000, v68
	v_cmp_gt_f32_e32 vcc, s6, v68
	s_nop 1
	v_cndmask_b32_e32 v68, v68, v69, vcc
	v_sqrt_f32_e32 v69, v68
	s_nop 0
	v_add_u32_e32 v62, -1, v69
	v_add_u32_e32 v63, 1, v69
	v_fma_f32 v71, -v62, v69, v68
	v_fma_f32 v74, -v63, v69, v68
	v_cmp_ge_f32_e64 s[6:7], 0, v71
	s_nop 1
	v_cndmask_b32_e64 v62, v69, v62, s[6:7]
	v_cmp_lt_f32_e64 s[6:7], 0, v74
	s_nop 1
	v_cndmask_b32_e64 v62, v62, v63, s[6:7]
	v_mul_f32_e32 v63, 0x37800000, v62
	v_cndmask_b32_e32 v62, v62, v63, vcc
	v_cmp_class_f32_e32 vcc, v68, v216
	s_nop 1
	v_cndmask_b32_e32 v68, v62, v68, vcc
	v_div_scale_f32 v69, s[6:7], v68, v68, 1.0
	v_rcp_f32_e32 v71, v69
	v_lshl_add_u64 v[62:63], s[18:19], 0, v[72:73]
	v_div_scale_f32 v72, vcc, 1.0, v68, 1.0
	v_fma_f32 v73, -v69, v71, 1.0
	v_fmac_f32_e32 v71, v73, v71
	v_mul_f32_e32 v73, v72, v71
	v_fma_f32 v74, -v69, v73, v72
	v_fmac_f32_e32 v73, v74, v71
	v_fma_f32 v69, -v69, v73, v72
	v_div_fmas_f32 v69, v69, v71, v73
	v_div_fixup_f32 v68, v69, v68, 1.0
	v_pk_mul_f32 v[60:61], v[60:61], v[68:69] op_sel_hi:[1,0]
	ds_write_b64 v70, v[60:61]
	global_store_dwordx2 v[62:63], v[60:61], off
.LBB0_334:
	s_or_b64 exec, exec, s[40:41]
	ds_bpermute_b32 v60, v2, v86
	ds_bpermute_b32 v61, v2, v87
	s_waitcnt lgkmcnt(0)
	v_pk_add_f32 v[60:61], v[86:87], v[60:61]
	ds_bpermute_b32 v62, v65, v60
	ds_bpermute_b32 v63, v65, v61
	s_waitcnt lgkmcnt(0)
	v_pk_add_f32 v[60:61], v[60:61], v[62:63]
	ds_bpermute_b32 v62, v66, v60
	ds_bpermute_b32 v63, v66, v61
	s_waitcnt lgkmcnt(0)
	v_pk_add_f32 v[60:61], v[60:61], v[62:63]
	ds_bpermute_b32 v62, v67, v60
	ds_bpermute_b32 v63, v67, v61
	s_and_saveexec_b64 s[6:7], s[4:5]
	s_cbranch_execz .LBB0_336
	v_add_u32_e32 v2, 0x60, v102
	v_add_u32_e32 v66, s63, v2
	v_ashrrev_i32_e32 v67, 31, v66
	v_lshlrev_b64 v[70:71], 4, v[66:67]
	v_lshl_add_u64 v[66:67], s[30:31], 0, v[70:71]
	s_mov_b32 s4, 0xf800000
	v_lshl_add_u32 v2, v2, 3, 0
	s_waitcnt lgkmcnt(0)
	v_pk_add_f32 v[60:61], v[60:61], v[62:63]
	v_mov_b64_e32 v[66:67], v[120:121]
	v_mov_b64_e32 v[68:69], v[122:123]
	v_mov_b32_e32 v72, v67
	v_mov_b32_e32 v73, v68
	v_mov_b32_e32 v67, v69
	v_pk_add_f32 v[66:67], v[72:73], v[66:67]
	s_nop 0
	v_add_f32_e32 v65, v66, v67
	v_fmamk_f32 v65, v65, 0x3a800000, v215
	v_mul_f32_e32 v66, 0x4f800000, v65
	v_cmp_gt_f32_e32 vcc, s4, v65
	v_add_u32_e32 v67, 0x22c00, v2
	s_nop 0
	v_cndmask_b32_e32 v65, v65, v66, vcc
	v_sqrt_f32_e32 v66, v65
	s_nop 0
	v_add_u32_e32 v2, -1, v66
	v_add_u32_e32 v62, 1, v66
	v_fma_f32 v63, -v2, v66, v65
	v_fma_f32 v68, -v62, v66, v65
	v_cmp_ge_f32_e64 s[4:5], 0, v63
	s_nop 1
	v_cndmask_b32_e64 v2, v66, v2, s[4:5]
	v_cmp_lt_f32_e64 s[4:5], 0, v68
	s_nop 1
	v_cndmask_b32_e64 v2, v2, v62, s[4:5]
	v_mul_f32_e32 v62, 0x37800000, v2
	v_cndmask_b32_e32 v2, v2, v62, vcc
	v_cmp_class_f32_e32 vcc, v65, v216
	v_lshl_add_u64 v[62:63], s[18:19], 0, v[70:71]
	s_nop 0
	v_cndmask_b32_e32 v2, v2, v65, vcc
	v_div_scale_f32 v65, s[4:5], v2, v2, 1.0
	v_rcp_f32_e32 v66, v65
	v_div_scale_f32 v68, vcc, 1.0, v2, 1.0
	v_fma_f32 v69, -v65, v66, 1.0
	v_fmac_f32_e32 v66, v69, v66
	v_mul_f32_e32 v69, v68, v66
	v_fma_f32 v70, -v65, v69, v68
	v_fmac_f32_e32 v69, v70, v66
	v_fma_f32 v65, -v65, v69, v68
	v_div_fmas_f32 v65, v65, v66, v69
	v_div_fixup_f32 v2, v65, v2, 1.0
	v_pk_mul_f32 v[60:61], v[60:61], v[2:3] op_sel_hi:[1,0]
	ds_write_b64 v67, v[60:61]
	global_store_dwordx2 v[62:63], v[60:61], off
